# GEMM mainloops: MFMA segments hold only MFMAs between their barriers - setprio 1 raised before the opening barrier, redundant post-barrier lgkmcnt(0) and mid-segment setprio pair dropped, setprio 0 mo
# speedup vs baseline: 1.0310x; 1.0310x over previous
; #define PG8_STAGE(bufoff, gbase, voff) do { _Pragma("unroll") for (int _i = 0; _i < 2; ++_i) \
;     __builtin_amdgcn_global_load_lds((const unsigned*)((const char*)(gbase) + (voff)[_i]), (LAS unsigned*)(lds + (bufoff) + ldsw + _i * 8192), 16, 0, 0); } while (0)
; #define PG8_LDA(dst, b, h) do { _Pragma("unroll") for (int m = 0; m < 4; ++m) _Pragma("unroll") for (int k = 0; k < 2; ++k) dst[m][k] = *(const LAS bf16x8*)(lds + PG8_SA(b, h) + aoff + m * 2048 + k * 1024); } while (0)
; #define PG8_LDB(dst, b, h) do { _Pragma("unroll") for (int n = 0; n < 2; ++n) _Pragma("unroll") for (int k = 0; k < 2; ++k) dst[n][k] = *(const LAS bf16x8*)(lds + PG8_SB(b, h) + boff + n * 2048 + k * 1024); } while (0)
; #define PG8_MMA(ai, bj, At, Bt) do { __builtin_amdgcn_s_setprio(1); _Pragma("unroll") for (int m = 0; m < 4; ++m) _Pragma("unroll") for (int n = 0; n < 2; ++n) _Pragma("unroll") for (int k = 0; k < 2; ++k) \
;     acc[ai][bj][m][n] = __builtin_amdgcn_mfma_f32_16x16x32_bf16(Bt[n][k], At[m][k], acc[ai][bj][m][n], 0, 0, 0); __builtin_amdgcn_s_setprio(0); } while (0)
; #define PG8_WAIT_V(n) asm volatile("s_waitcnt vmcnt(" #n ")" ::: "memory")
; #define PG8_WAIT_L(n) asm volatile("s_waitcnt lgkmcnt(" #n ")" ::: "memory")
; #define PG8_BAR __builtin_amdgcn_s_barrier()
; #define PG8_SCHED __builtin_amdgcn_sched_barrier(0)
; template <class Epi>
; DI void gemm_phase(LAS unsigned char* lds, const Gemm g, const StaticOrder& S, const Epi& E) {
;     ...
;     for (int t = 0; t < nt; t += 2) {
;       const bool last = (t == nt - 2);
;       const char* a1 = cA + (size_t)(t + 1) * kstep;
;       const char* a2 = last ? nA : cA + (size_t)(t + 2) * kstep; const char* b2 = last ? nB : cB + (size_t)(t + 2) * kstep;
;       const char* a3 = a2 + kstep; const char* b3 = b2 + kstep;
;       PG8_LDB(B0, 0, 0); PG8_LDB(B1, 0, 1); PG8_SCHED; PG8_LDA(At, 0, 0); PG8_STAGE(PG8_SA(1, 1), a1 + hstepA, voffA);
;       PG8_WAIT_V(8); PG8_WAIT_L(0); PG8_BAR; PG8_MMA(0, 0, At, B0); PG8_MMA(0, 1, At, B1); PG8_BAR; PG8_SCHED;
;       PG8_LDA(At, 0, 1); PG8_STAGE(PG8_SB(0, 0), b2, voffB); PG8_STAGE(PG8_SB(0, 1), b2 + hstepB, voffB); PG8_STAGE(PG8_SA(0, 0), a2, voffA);
;       PG8_WAIT_V(8); PG8_WAIT_L(0); PG8_BAR; PG8_MMA(1, 0, At, B0); PG8_MMA(1, 1, At, B1); PG8_BAR; PG8_SCHED;
.LBB0_329:
	s_add_i32 vcc_lo, s46, 2
	s_add_u32 s4, s44, 0x80
	s_addc_u32 s5, s45, 0
	s_add_i32 vcc_hi, 0, 0x10000
	s_cmp_eq_u32 s63, s46
	s_cselect_b32 s47, s83, s5
	s_cselect_b32 s46, s82, s4
	s_cselect_b32 s5, s85, s49
	s_cselect_b32 s4, s84, s48
	s_add_i32 s13, 0, 0x14000
	v_add_u32_e32 v142, vcc_hi, v184
	v_add_u32_e32 v158, s13, v184
	ds_read_b128 v[130:133], v142
	ds_read_b128 v[134:137], v142 offset:1024
	ds_read_b128 v[138:141], v142 offset:2048
	ds_read_b128 v[142:145], v142 offset:3072
	ds_read_b128 v[146:149], v158
	ds_read_b128 v[150:153], v158 offset:1024
	ds_read_b128 v[154:157], v158 offset:2048
	ds_read_b128 v[158:161], v158 offset:3072
	v_lshl_add_u64 v[226:227], s[44:45], 0, v[172:173]
	s_add_i32 m0, s16, 0xc000
	ds_read_b128 v[176:179], v204
	ds_read_b128 v[180:183], v204 offset:1024
	ds_read_b128 v[206:209], v204 offset:2048
	ds_read_b128 v[210:213], v204 offset:3072
	ds_read_b128 v[214:217], v204 offset:4096
	ds_read_b128 v[218:221], v204 offset:5120
	ds_read_b128 v[222:225], v204 offset:6144
	ds_read_b128 v[230:233], v204 offset:7168
	global_load_lds_dwordx4 v[226:227], off
	v_lshl_add_u64 v[226:227], s[44:45], 0, v[174:175]
	s_add_i32 m0, s16, 0xe000
	s_nop 0
	global_load_lds_dwordx4 v[226:227], off
	s_waitcnt vmcnt(8)
	s_waitcnt lgkmcnt(0)
	s_setprio 1
	s_barrier
	v_mfma_f32_16x16x32_bf16 v[126:129], v[130:133], v[176:179], v[126:129]
	v_mfma_f32_16x16x32_bf16 v[122:125], v[138:141], v[176:179], v[122:125]
	v_mfma_f32_16x16x32_bf16 v[110:113], v[130:133], v[206:209], v[110:113]
	v_mfma_f32_16x16x32_bf16 v[106:109], v[138:141], v[206:209], v[106:109]
	v_mfma_f32_16x16x32_bf16 v[94:97], v[130:133], v[214:217], v[94:97]
	v_mfma_f32_16x16x32_bf16 v[90:93], v[138:141], v[214:217], v[90:93]
	v_mfma_f32_16x16x32_bf16 v[78:81], v[130:133], v[222:225], v[78:81]
	v_mfma_f32_16x16x32_bf16 v[74:77], v[138:141], v[222:225], v[74:77]
	v_mfma_f32_16x16x32_bf16 v[126:129], v[134:137], v[180:183], v[126:129]
	v_mfma_f32_16x16x32_bf16 v[122:125], v[142:145], v[180:183], v[122:125]
	v_mfma_f32_16x16x32_bf16 v[110:113], v[134:137], v[210:213], v[110:113]
	v_mfma_f32_16x16x32_bf16 v[106:109], v[142:145], v[210:213], v[106:109]
	v_mfma_f32_16x16x32_bf16 v[94:97], v[134:137], v[218:221], v[94:97]
	v_mfma_f32_16x16x32_bf16 v[90:93], v[142:145], v[218:221], v[90:93]
	v_mfma_f32_16x16x32_bf16 v[78:81], v[134:137], v[230:233], v[78:81]
	v_mfma_f32_16x16x32_bf16 v[74:77], v[142:145], v[230:233], v[74:77]
	v_mfma_f32_16x16x32_bf16 v[118:121], v[146:149], v[176:179], v[118:121]
	v_mfma_f32_16x16x32_bf16 v[114:117], v[154:157], v[176:179], v[114:117]
	v_mfma_f32_16x16x32_bf16 v[102:105], v[146:149], v[206:209], v[102:105]
	v_mfma_f32_16x16x32_bf16 v[98:101], v[154:157], v[206:209], v[98:101]
	v_mfma_f32_16x16x32_bf16 v[86:89], v[146:149], v[214:217], v[86:89]
	v_mfma_f32_16x16x32_bf16 v[82:85], v[154:157], v[214:217], v[82:85]
	v_mfma_f32_16x16x32_bf16 v[70:73], v[146:149], v[222:225], v[70:73]
	v_mfma_f32_16x16x32_bf16 v[66:69], v[154:157], v[222:225], v[66:69]
	v_mfma_f32_16x16x32_bf16 v[118:121], v[150:153], v[180:183], v[118:121]
	v_mfma_f32_16x16x32_bf16 v[114:117], v[158:161], v[180:183], v[114:117]
	v_mfma_f32_16x16x32_bf16 v[102:105], v[150:153], v[210:213], v[102:105]
	v_mfma_f32_16x16x32_bf16 v[98:101], v[158:161], v[210:213], v[98:101]
	v_mfma_f32_16x16x32_bf16 v[86:89], v[150:153], v[218:221], v[86:89]
	v_mfma_f32_16x16x32_bf16 v[82:85], v[158:161], v[218:221], v[82:85]
	v_mfma_f32_16x16x32_bf16 v[70:73], v[150:153], v[230:233], v[70:73]
	v_mfma_f32_16x16x32_bf16 v[66:69], v[158:161], v[230:233], v[66:69]
	s_barrier
	s_setprio 0
	s_add_i32 vcc_hi, vcc_hi, s3
	v_lshl_add_u64 v[226:227], s[4:5], 0, v[0:1]
	s_mov_b32 m0, vcc_hi
	ds_read_b128 v[176:179], v204 offset:16384
	ds_read_b128 v[180:183], v204 offset:17408
	ds_read_b128 v[206:209], v204 offset:18432
	ds_read_b128 v[210:213], v204 offset:19456
	ds_read_b128 v[214:217], v204 offset:20480
	ds_read_b128 v[218:221], v204 offset:21504
	ds_read_b128 v[222:225], v204 offset:22528
	ds_read_b128 v[230:233], v204 offset:23552
	global_load_lds_dwordx4 v[226:227], off
	s_add_i32 m0, vcc_hi, 0x2000
	v_lshl_add_u64 v[234:235], s[4:5], 0, v[170:171]
	s_add_u32 s4, s4, s10
	s_addc_u32 s5, s5, s11
	s_add_i32 s13, s13, s3
	global_load_lds_dwordx4 v[234:235], off
	v_lshl_add_u64 v[236:237], s[4:5], 0, v[0:1]
	s_mov_b32 m0, s13
	v_lshl_add_u64 v[238:239], s[4:5], 0, v[170:171]
	global_load_lds_dwordx4 v[236:237], off
	s_add_i32 m0, s13, 0x2000
	v_lshl_add_u64 v[240:241], s[46:47], 0, v[166:167]
	global_load_lds_dwordx4 v[238:239], off
	s_mov_b32 m0, s16
	v_lshl_add_u64 v[242:243], s[46:47], 0, v[168:169]
	global_load_lds_dwordx4 v[240:241], off
	s_mov_b32 m0, s17
	s_nop 0
	global_load_lds_dwordx4 v[242:243], off
	s_waitcnt vmcnt(8)
	s_waitcnt lgkmcnt(0)
	s_setprio 1
	s_barrier
; #define PG8_STAGE(bufoff, gbase, voff) do { _Pragma("unroll") for (int _i = 0; _i < 2; ++_i) \
;     __builtin_amdgcn_global_load_lds((const unsigned*)((const char*)(gbase) + (voff)[_i]), (LAS unsigned*)(lds + (bufoff) + ldsw + _i * 8192), 16, 0, 0); } while (0)
; #define PG8_LDA(dst, b, h) do { _Pragma("unroll") for (int m = 0; m < 4; ++m) _Pragma("unroll") for (int k = 0; k < 2; ++k) dst[m][k] = *(const LAS bf16x8*)(lds + PG8_SA(b, h) + aoff + m * 2048 + k * 1024); } while (0)
; #define PG8_LDB(dst, b, h) do { _Pragma("unroll") for (int n = 0; n < 2; ++n) _Pragma("unroll") for (int k = 0; k < 2; ++k) dst[n][k] = *(const LAS bf16x8*)(lds + PG8_SB(b, h) + boff + n * 2048 + k * 1024); } while (0)
; #define PG8_MMA(ai, bj, At, Bt) do { __builtin_amdgcn_s_setprio(1); _Pragma("unroll") for (int m = 0; m < 4; ++m) _Pragma("unroll") for (int n = 0; n < 2; ++n) _Pragma("unroll") for (int k = 0; k < 2; ++k) \
;     acc[ai][bj][m][n] = __builtin_amdgcn_mfma_f32_16x16x32_bf16(Bt[n][k], At[m][k], acc[ai][bj][m][n], 0, 0, 0); __builtin_amdgcn_s_setprio(0); } while (0)
; #define PG8_WAIT_V(n) asm volatile("s_waitcnt vmcnt(" #n ")" ::: "memory")
; #define PG8_WAIT_L(n) asm volatile("s_waitcnt lgkmcnt(" #n ")" ::: "memory")
; #define PG8_BAR __builtin_amdgcn_s_barrier()
; #define PG8_SCHED __builtin_amdgcn_sched_barrier(0)
; template <class Epi>
; DI void gemm_phase(LAS unsigned char* lds, const Gemm g, const StaticOrder& S, const Epi& E) {
;     ...
;       PG8_WAIT_V(8); PG8_WAIT_L(0); PG8_BAR; PG8_MMA(1, 0, At, B0); PG8_MMA(1, 1, At, B1); PG8_BAR; PG8_SCHED;
;       PG8_LDB(B0, 1, 0); PG8_LDB(B1, 1, 1); PG8_SCHED; PG8_LDA(At, 1, 0); PG8_STAGE(PG8_SA(0, 1), a2 + hstepA, voffA);
;       PG8_WAIT_V(8); PG8_WAIT_L(0); PG8_BAR; PG8_MMA(0, 0, At, B0); PG8_MMA(0, 1, At, B1); PG8_BAR; PG8_SCHED;
;       PG8_LDA(At, 1, 1); PG8_STAGE(PG8_SB(1, 0), b3, voffB); PG8_STAGE(PG8_SB(1, 1), b3 + hstepB, voffB); PG8_STAGE(PG8_SA(1, 0), a3, voffA);
;       PG8_WAIT_V(8); PG8_WAIT_L(0); PG8_BAR; PG8_MMA(1, 0, At, B0); PG8_MMA(1, 1, At, B1); PG8_BAR; PG8_SCHED;
	v_mfma_f32_16x16x32_bf16 v[62:65], v[130:133], v[176:179], v[62:65]
	v_mfma_f32_16x16x32_bf16 v[58:61], v[138:141], v[176:179], v[58:61]
	v_mfma_f32_16x16x32_bf16 v[46:49], v[130:133], v[206:209], v[46:49]
	v_mfma_f32_16x16x32_bf16 v[42:45], v[138:141], v[206:209], v[42:45]
	v_mfma_f32_16x16x32_bf16 v[30:33], v[130:133], v[214:217], v[30:33]
	v_mfma_f32_16x16x32_bf16 v[26:29], v[138:141], v[214:217], v[26:29]
	v_mfma_f32_16x16x32_bf16 v[14:17], v[130:133], v[222:225], v[14:17]
	v_mfma_f32_16x16x32_bf16 v[10:13], v[138:141], v[222:225], v[10:13]
	v_mfma_f32_16x16x32_bf16 v[62:65], v[134:137], v[180:183], v[62:65]
	v_mfma_f32_16x16x32_bf16 v[58:61], v[142:145], v[180:183], v[58:61]
	v_mfma_f32_16x16x32_bf16 v[46:49], v[134:137], v[210:213], v[46:49]
	v_mfma_f32_16x16x32_bf16 v[42:45], v[142:145], v[210:213], v[42:45]
	v_mfma_f32_16x16x32_bf16 v[30:33], v[134:137], v[218:221], v[30:33]
	v_mfma_f32_16x16x32_bf16 v[26:29], v[142:145], v[218:221], v[26:29]
	v_mfma_f32_16x16x32_bf16 v[14:17], v[134:137], v[230:233], v[14:17]
	v_mfma_f32_16x16x32_bf16 v[10:13], v[142:145], v[230:233], v[10:13]
	v_mfma_f32_16x16x32_bf16 v[54:57], v[146:149], v[176:179], v[54:57]
	v_mfma_f32_16x16x32_bf16 v[50:53], v[154:157], v[176:179], v[50:53]
	v_mfma_f32_16x16x32_bf16 v[38:41], v[146:149], v[206:209], v[38:41]
	v_mfma_f32_16x16x32_bf16 v[34:37], v[154:157], v[206:209], v[34:37]
	v_mfma_f32_16x16x32_bf16 v[22:25], v[146:149], v[214:217], v[22:25]
	v_mfma_f32_16x16x32_bf16 v[18:21], v[154:157], v[214:217], v[18:21]
	v_mfma_f32_16x16x32_bf16 v[6:9], v[146:149], v[222:225], v[6:9]
	v_mfma_f32_16x16x32_bf16 v[2:5], v[154:157], v[222:225], v[2:5]
	v_mfma_f32_16x16x32_bf16 v[54:57], v[150:153], v[180:183], v[54:57]
	v_mfma_f32_16x16x32_bf16 v[50:53], v[158:161], v[180:183], v[50:53]
	v_mfma_f32_16x16x32_bf16 v[38:41], v[150:153], v[210:213], v[38:41]
	v_mfma_f32_16x16x32_bf16 v[34:37], v[158:161], v[210:213], v[34:37]
	v_mfma_f32_16x16x32_bf16 v[22:25], v[150:153], v[218:221], v[22:25]
	v_mfma_f32_16x16x32_bf16 v[18:21], v[158:161], v[218:221], v[18:21]
	v_mfma_f32_16x16x32_bf16 v[6:9], v[150:153], v[230:233], v[6:9]
	v_mfma_f32_16x16x32_bf16 v[2:5], v[158:161], v[230:233], v[2:5]
	s_barrier
	s_setprio 0
	s_add_i32 s13, 0, 0x18000
	s_add_i32 vcc_hi, 0, 0x1c000
	v_add_u32_e32 v142, s13, v184
	v_add_u32_e32 v158, vcc_hi, v184
	ds_read_b128 v[130:133], v142
	ds_read_b128 v[134:137], v142 offset:1024
	ds_read_b128 v[138:141], v142 offset:2048
	ds_read_b128 v[142:145], v142 offset:3072
	ds_read_b128 v[146:149], v158
	ds_read_b128 v[150:153], v158 offset:1024
	ds_read_b128 v[154:157], v158 offset:2048
	ds_read_b128 v[158:161], v158 offset:3072
	s_add_u32 s4, s46, s8
	s_addc_u32 s5, s47, s9
	s_mov_b32 m0, s33
	v_lshl_add_u64 v[244:245], s[4:5], 0, v[166:167]
	ds_read_b128 v[176:179], v204 offset:32768
	ds_read_b128 v[180:183], v204 offset:33792
	ds_read_b128 v[206:209], v204 offset:34816
	ds_read_b128 v[210:213], v204 offset:35840
	ds_read_b128 v[214:217], v204 offset:36864
	ds_read_b128 v[218:221], v204 offset:37888
	ds_read_b128 v[222:225], v204 offset:38912
	ds_read_b128 v[230:233], v204 offset:39936
	global_load_lds_dwordx4 v[244:245], off
	v_lshl_add_u64 v[244:245], s[4:5], 0, v[168:169]
	s_mov_b32 m0, s56
	s_nop 0
	global_load_lds_dwordx4 v[244:245], off
	s_waitcnt vmcnt(8)
	s_waitcnt lgkmcnt(0)
	s_setprio 1
	s_barrier
	v_mfma_f32_16x16x32_bf16 v[126:129], v[130:133], v[176:179], v[126:129]
	v_mfma_f32_16x16x32_bf16 v[122:125], v[138:141], v[176:179], v[122:125]
	v_mfma_f32_16x16x32_bf16 v[110:113], v[130:133], v[206:209], v[110:113]
	v_mfma_f32_16x16x32_bf16 v[106:109], v[138:141], v[206:209], v[106:109]
	v_mfma_f32_16x16x32_bf16 v[94:97], v[130:133], v[214:217], v[94:97]
	v_mfma_f32_16x16x32_bf16 v[90:93], v[138:141], v[214:217], v[90:93]
	v_mfma_f32_16x16x32_bf16 v[78:81], v[130:133], v[222:225], v[78:81]
	v_mfma_f32_16x16x32_bf16 v[74:77], v[138:141], v[222:225], v[74:77]
	v_mfma_f32_16x16x32_bf16 v[126:129], v[134:137], v[180:183], v[126:129]
	v_mfma_f32_16x16x32_bf16 v[122:125], v[142:145], v[180:183], v[122:125]
	v_mfma_f32_16x16x32_bf16 v[110:113], v[134:137], v[210:213], v[110:113]
	v_mfma_f32_16x16x32_bf16 v[106:109], v[142:145], v[210:213], v[106:109]
	v_mfma_f32_16x16x32_bf16 v[94:97], v[134:137], v[218:221], v[94:97]
	v_mfma_f32_16x16x32_bf16 v[90:93], v[142:145], v[218:221], v[90:93]
	v_mfma_f32_16x16x32_bf16 v[78:81], v[134:137], v[230:233], v[78:81]
	v_mfma_f32_16x16x32_bf16 v[74:77], v[142:145], v[230:233], v[74:77]
	v_mfma_f32_16x16x32_bf16 v[118:121], v[146:149], v[176:179], v[118:121]
	v_mfma_f32_16x16x32_bf16 v[114:117], v[154:157], v[176:179], v[114:117]
	v_mfma_f32_16x16x32_bf16 v[102:105], v[146:149], v[206:209], v[102:105]
	v_mfma_f32_16x16x32_bf16 v[98:101], v[154:157], v[206:209], v[98:101]
	v_mfma_f32_16x16x32_bf16 v[86:89], v[146:149], v[214:217], v[86:89]
	v_mfma_f32_16x16x32_bf16 v[82:85], v[154:157], v[214:217], v[82:85]
	v_mfma_f32_16x16x32_bf16 v[70:73], v[146:149], v[222:225], v[70:73]
	v_mfma_f32_16x16x32_bf16 v[66:69], v[154:157], v[222:225], v[66:69]
	v_mfma_f32_16x16x32_bf16 v[118:121], v[150:153], v[180:183], v[118:121]
	v_mfma_f32_16x16x32_bf16 v[114:117], v[158:161], v[180:183], v[114:117]
	v_mfma_f32_16x16x32_bf16 v[102:105], v[150:153], v[210:213], v[102:105]
	v_mfma_f32_16x16x32_bf16 v[98:101], v[158:161], v[210:213], v[98:101]
	v_mfma_f32_16x16x32_bf16 v[86:89], v[150:153], v[218:221], v[86:89]
	v_mfma_f32_16x16x32_bf16 v[82:85], v[158:161], v[218:221], v[82:85]
	v_mfma_f32_16x16x32_bf16 v[70:73], v[150:153], v[230:233], v[70:73]
	v_mfma_f32_16x16x32_bf16 v[66:69], v[158:161], v[230:233], v[66:69]
	s_barrier
; #define PG8_STAGE(bufoff, gbase, voff) do { _Pragma("unroll") for (int _i = 0; _i < 2; ++_i) \
;     __builtin_amdgcn_global_load_lds((const unsigned*)((const char*)(gbase) + (voff)[_i]), (LAS unsigned*)(lds + (bufoff) + ldsw + _i * 8192), 16, 0, 0); } while (0)
; #define PG8_LDA(dst, b, h) do { _Pragma("unroll") for (int m = 0; m < 4; ++m) _Pragma("unroll") for (int k = 0; k < 2; ++k) dst[m][k] = *(const LAS bf16x8*)(lds + PG8_SA(b, h) + aoff + m * 2048 + k * 1024); } while (0)
; #define PG8_MMA(ai, bj, At, Bt) do { __builtin_amdgcn_s_setprio(1); _Pragma("unroll") for (int m = 0; m < 4; ++m) _Pragma("unroll") for (int n = 0; n < 2; ++n) _Pragma("unroll") for (int k = 0; k < 2; ++k) \
;     acc[ai][bj][m][n] = __builtin_amdgcn_mfma_f32_16x16x32_bf16(Bt[n][k], At[m][k], acc[ai][bj][m][n], 0, 0, 0); __builtin_amdgcn_s_setprio(0); } while (0)
; #define PG8_WAIT_V(n) asm volatile("s_waitcnt vmcnt(" #n ")" ::: "memory")
; #define PG8_WAIT_L(n) asm volatile("s_waitcnt lgkmcnt(" #n ")" ::: "memory")
; #define PG8_BAR __builtin_amdgcn_s_barrier()
; #define PG8_SCHED __builtin_amdgcn_sched_barrier(0)
; template <class Epi>
; DI void gemm_phase(LAS unsigned char* lds, const Gemm g, const StaticOrder& S, const Epi& E) {
;     ...
;     for (int t = 0; t < nt; t += 2) {
;       const bool last = (t == nt - 2);
;       const char* a1 = cA + (size_t)(t + 1) * kstep;
;       const char* a2 = last ? nA : cA + (size_t)(t + 2) * kstep; const char* b2 = last ? nB : cB + (size_t)(t + 2) * kstep;
;       const char* a3 = a2 + kstep; const char* b3 = b2 + kstep;
;     ...
;       PG8_LDA(At, 1, 1); PG8_STAGE(PG8_SB(1, 0), b3, voffB); PG8_STAGE(PG8_SB(1, 1), b3 + hstepB, voffB); PG8_STAGE(PG8_SA(1, 0), a3, voffA);
;       PG8_WAIT_V(8); PG8_WAIT_L(0); PG8_BAR; PG8_MMA(1, 0, At, B0); PG8_MMA(1, 1, At, B1); PG8_BAR; PG8_SCHED;
	s_setprio 0
	s_add_i32 s4, s13, s3
	v_lshl_add_u64 v[226:227], v[226:227], 0, s[38:39]
	s_mov_b32 m0, s4
	ds_read_b128 v[176:179], v204 offset:49152
	ds_read_b128 v[180:183], v204 offset:50176
	ds_read_b128 v[206:209], v204 offset:51200
	ds_read_b128 v[210:213], v204 offset:52224
	ds_read_b128 v[214:217], v204 offset:53248
	ds_read_b128 v[218:221], v204 offset:54272
	ds_read_b128 v[222:225], v204 offset:55296
	ds_read_b128 v[230:233], v204 offset:56320
	global_load_lds_dwordx4 v[226:227], off
	v_lshl_add_u64 v[226:227], v[234:235], 0, s[38:39]
	s_add_i32 m0, s4, 0x2000
	s_add_i32 s4, vcc_hi, s3
	global_load_lds_dwordx4 v[226:227], off
	v_lshl_add_u64 v[226:227], v[236:237], 0, s[38:39]
	s_mov_b32 m0, s4
	s_nop 0
	global_load_lds_dwordx4 v[226:227], off
	v_lshl_add_u64 v[226:227], v[238:239], 0, s[38:39]
	s_add_i32 m0, s4, 0x2000
	s_nop 0
	global_load_lds_dwordx4 v[226:227], off
	v_lshl_add_u64 v[226:227], v[240:241], 0, s[38:39]
	s_mov_b32 m0, s58
	s_nop 0
	global_load_lds_dwordx4 v[226:227], off
	v_lshl_add_u64 v[226:227], v[242:243], 0, s[38:39]
	s_mov_b32 m0, s62
	s_nop 0
	global_load_lds_dwordx4 v[226:227], off
	s_waitcnt vmcnt(8)
	s_waitcnt lgkmcnt(0)
	s_setprio 1
	s_barrier
	v_mfma_f32_16x16x32_bf16 v[62:65], v[130:133], v[176:179], v[62:65]
	v_mfma_f32_16x16x32_bf16 v[58:61], v[138:141], v[176:179], v[58:61]
	v_mfma_f32_16x16x32_bf16 v[46:49], v[130:133], v[206:209], v[46:49]
	v_mfma_f32_16x16x32_bf16 v[42:45], v[138:141], v[206:209], v[42:45]
	v_mfma_f32_16x16x32_bf16 v[30:33], v[130:133], v[214:217], v[30:33]
	v_mfma_f32_16x16x32_bf16 v[26:29], v[138:141], v[214:217], v[26:29]
	v_mfma_f32_16x16x32_bf16 v[14:17], v[130:133], v[222:225], v[14:17]
	v_mfma_f32_16x16x32_bf16 v[10:13], v[138:141], v[222:225], v[10:13]
	v_mfma_f32_16x16x32_bf16 v[62:65], v[134:137], v[180:183], v[62:65]
	v_mfma_f32_16x16x32_bf16 v[58:61], v[142:145], v[180:183], v[58:61]
	v_mfma_f32_16x16x32_bf16 v[46:49], v[134:137], v[210:213], v[46:49]
	v_mfma_f32_16x16x32_bf16 v[42:45], v[142:145], v[210:213], v[42:45]
	v_mfma_f32_16x16x32_bf16 v[30:33], v[134:137], v[218:221], v[30:33]
	v_mfma_f32_16x16x32_bf16 v[26:29], v[142:145], v[218:221], v[26:29]
	v_mfma_f32_16x16x32_bf16 v[14:17], v[134:137], v[230:233], v[14:17]
	v_mfma_f32_16x16x32_bf16 v[10:13], v[142:145], v[230:233], v[10:13]
	v_mfma_f32_16x16x32_bf16 v[54:57], v[146:149], v[176:179], v[54:57]
	v_mfma_f32_16x16x32_bf16 v[50:53], v[154:157], v[176:179], v[50:53]
	v_mfma_f32_16x16x32_bf16 v[38:41], v[146:149], v[206:209], v[38:41]
	v_mfma_f32_16x16x32_bf16 v[34:37], v[154:157], v[206:209], v[34:37]
	v_mfma_f32_16x16x32_bf16 v[22:25], v[146:149], v[214:217], v[22:25]
	v_mfma_f32_16x16x32_bf16 v[18:21], v[154:157], v[214:217], v[18:21]
	v_mfma_f32_16x16x32_bf16 v[6:9], v[146:149], v[222:225], v[6:9]
	v_mfma_f32_16x16x32_bf16 v[2:5], v[154:157], v[222:225], v[2:5]
	v_mfma_f32_16x16x32_bf16 v[54:57], v[150:153], v[180:183], v[54:57]
	v_mfma_f32_16x16x32_bf16 v[50:53], v[158:161], v[180:183], v[50:53]
	v_mfma_f32_16x16x32_bf16 v[38:41], v[150:153], v[210:213], v[38:41]
	v_mfma_f32_16x16x32_bf16 v[34:37], v[158:161], v[210:213], v[34:37]
	v_mfma_f32_16x16x32_bf16 v[22:25], v[150:153], v[218:221], v[22:25]
	v_mfma_f32_16x16x32_bf16 v[18:21], v[158:161], v[218:221], v[18:21]
	v_mfma_f32_16x16x32_bf16 v[6:9], v[150:153], v[230:233], v[6:9]
	v_mfma_f32_16x16x32_bf16 v[2:5], v[158:161], v[230:233], v[2:5]
	s_barrier
	s_setprio 0
	s_add_u32 s44, s44, 0x100
	s_addc_u32 s45, s45, 0
	s_add_u32 s48, s48, 0x100
	s_addc_u32 s49, s49, 0
	s_cmp_ge_i32 vcc_lo, s57
	s_mov_b32 s46, vcc_lo
	s_cbranch_scc0 .LBB0_329

; #define PG8_STAGE(bufoff, gbase, voff) do { _Pragma("unroll") for (int _i = 0; _i < 2; ++_i) \
;     __builtin_amdgcn_global_load_lds((const unsigned*)((const char*)(gbase) + (voff)[_i]), (LAS unsigned*)(lds + (bufoff) + ldsw + _i * 8192), 16, 0, 0); } while (0)
; #define PG8_LDA(dst, b, h) do { _Pragma("unroll") for (int m = 0; m < 4; ++m) _Pragma("unroll") for (int k = 0; k < 2; ++k) dst[m][k] = *(const LAS bf16x8*)(lds + PG8_SA(b, h) + aoff + m * 2048 + k * 1024); } while (0)
; #define PG8_LDB(dst, b, h) do { _Pragma("unroll") for (int n = 0; n < 2; ++n) _Pragma("unroll") for (int k = 0; k < 2; ++k) dst[n][k] = *(const LAS bf16x8*)(lds + PG8_SB(b, h) + boff + n * 2048 + k * 1024); } while (0)
; #define PG8_MMA(ai, bj, At, Bt) do { __builtin_amdgcn_s_setprio(1); _Pragma("unroll") for (int m = 0; m < 4; ++m) _Pragma("unroll") for (int n = 0; n < 2; ++n) _Pragma("unroll") for (int k = 0; k < 2; ++k) \
;     acc[ai][bj][m][n] = __builtin_amdgcn_mfma_f32_16x16x32_bf16(Bt[n][k], At[m][k], acc[ai][bj][m][n], 0, 0, 0); __builtin_amdgcn_s_setprio(0); } while (0)
; #define PG8_WAIT_V(n) asm volatile("s_waitcnt vmcnt(" #n ")" ::: "memory")
; #define PG8_WAIT_L(n) asm volatile("s_waitcnt lgkmcnt(" #n ")" ::: "memory")
; #define PG8_BAR __builtin_amdgcn_s_barrier()
; #define PG8_SCHED __builtin_amdgcn_sched_barrier(0)
; template <class Epi>
; DI void gemm_phase(LAS unsigned char* lds, const Gemm g, const StaticOrder& S, const Epi& E) {
;     ...
;     for (int t = 0; t < nt; t += 2) {
;       const bool last = (t == nt - 2);
;       const char* a1 = cA + (size_t)(t + 1) * kstep;
;       const char* a2 = last ? nA : cA + (size_t)(t + 2) * kstep; const char* b2 = last ? nB : cB + (size_t)(t + 2) * kstep;
;       const char* a3 = a2 + kstep; const char* b3 = b2 + kstep;
;       PG8_LDB(B0, 0, 0); PG8_LDB(B1, 0, 1); PG8_SCHED; PG8_LDA(At, 0, 0); PG8_STAGE(PG8_SA(1, 1), a1 + hstepA, voffA);
;       PG8_WAIT_V(8); PG8_WAIT_L(0); PG8_BAR; PG8_MMA(0, 0, At, B0); PG8_MMA(0, 1, At, B1); PG8_BAR; PG8_SCHED;
;       PG8_LDA(At, 0, 1); PG8_STAGE(PG8_SB(0, 0), b2, voffB); PG8_STAGE(PG8_SB(0, 1), b2 + hstepB, voffB); PG8_STAGE(PG8_SA(0, 0), a2, voffA);
;       PG8_WAIT_V(8); PG8_WAIT_L(0); PG8_BAR; PG8_MMA(1, 0, At, B0); PG8_MMA(1, 1, At, B1); PG8_BAR; PG8_SCHED;
.LBB0_555:
	s_add_i32 s87, s54, 2
	s_add_u32 s88, s42, 0x80
	s_addc_u32 s55, s43, 0
	s_add_i32 s94, 0, 0x10000
	s_cmp_eq_u32 s69, s54
	s_cselect_b32 s55, s21, s55
	s_cselect_b32 s54, s20, s88
	s_cselect_b32 s89, s23, s63
	s_cselect_b32 s88, s22, s62
	s_add_i32 s95, 0, 0x14000
	v_add_u32_e32 v54, s94, v182
	v_add_u32_e32 v158, s95, v182
	ds_read_b128 v[34:37], v54
	ds_read_b128 v[42:45], v54 offset:1024
	ds_read_b128 v[50:53], v54 offset:2048
	ds_read_b128 v[54:57], v54 offset:3072
	ds_read_b128 v[62:65], v158
	ds_read_b128 v[66:69], v158 offset:1024
	ds_read_b128 v[154:157], v158 offset:2048
	ds_read_b128 v[158:161], v158 offset:3072
	v_lshl_add_u64 v[180:181], s[42:43], 0, v[172:173]
	s_add_i32 m0, s16, 0xc000
	ds_read_b128 v[176:179], v184
	ds_read_b128 v[204:207], v184 offset:1024
	ds_read_b128 v[208:211], v184 offset:2048
	ds_read_b128 v[212:215], v184 offset:3072
	ds_read_b128 v[216:219], v184 offset:4096
	ds_read_b128 v[220:223], v184 offset:5120
	ds_read_b128 v[224:227], v184 offset:6144
	ds_read_b128 v[230:233], v184 offset:7168
	global_load_lds_dwordx4 v[180:181], off
	v_lshl_add_u64 v[180:181], s[42:43], 0, v[174:175]
	s_add_i32 m0, s16, 0xe000
	s_nop 0
	global_load_lds_dwordx4 v[180:181], off
	s_waitcnt vmcnt(8)
	s_waitcnt lgkmcnt(0)
	s_setprio 1
	s_barrier
	v_mfma_f32_16x16x32_bf16 v[150:153], v[34:37], v[176:179], v[150:153]
	v_mfma_f32_16x16x32_bf16 v[146:149], v[50:53], v[176:179], v[146:149]
	v_mfma_f32_16x16x32_bf16 v[134:137], v[34:37], v[208:211], v[134:137]
	v_mfma_f32_16x16x32_bf16 v[130:133], v[50:53], v[208:211], v[130:133]
	v_mfma_f32_16x16x32_bf16 v[118:121], v[34:37], v[216:219], v[118:121]
	v_mfma_f32_16x16x32_bf16 v[114:117], v[50:53], v[216:219], v[114:117]
	v_mfma_f32_16x16x32_bf16 v[102:105], v[34:37], v[224:227], v[102:105]
	v_mfma_f32_16x16x32_bf16 v[98:101], v[50:53], v[224:227], v[98:101]
	v_mfma_f32_16x16x32_bf16 v[150:153], v[42:45], v[204:207], v[150:153]
	v_mfma_f32_16x16x32_bf16 v[146:149], v[54:57], v[204:207], v[146:149]
	v_mfma_f32_16x16x32_bf16 v[134:137], v[42:45], v[212:215], v[134:137]
	v_mfma_f32_16x16x32_bf16 v[130:133], v[54:57], v[212:215], v[130:133]
	v_mfma_f32_16x16x32_bf16 v[118:121], v[42:45], v[220:223], v[118:121]
	v_mfma_f32_16x16x32_bf16 v[114:117], v[54:57], v[220:223], v[114:117]
	v_mfma_f32_16x16x32_bf16 v[102:105], v[42:45], v[230:233], v[102:105]
	v_mfma_f32_16x16x32_bf16 v[98:101], v[54:57], v[230:233], v[98:101]
	v_mfma_f32_16x16x32_bf16 v[138:141], v[62:65], v[176:179], v[138:141]
	v_mfma_f32_16x16x32_bf16 v[142:145], v[154:157], v[176:179], v[142:145]
	v_mfma_f32_16x16x32_bf16 v[122:125], v[62:65], v[208:211], v[122:125]
	v_mfma_f32_16x16x32_bf16 v[126:129], v[154:157], v[208:211], v[126:129]
	v_mfma_f32_16x16x32_bf16 v[106:109], v[62:65], v[216:219], v[106:109]
	v_mfma_f32_16x16x32_bf16 v[110:113], v[154:157], v[216:219], v[110:113]
	v_mfma_f32_16x16x32_bf16 v[90:93], v[62:65], v[224:227], v[90:93]
	v_mfma_f32_16x16x32_bf16 v[94:97], v[154:157], v[224:227], v[94:97]
	v_mfma_f32_16x16x32_bf16 v[138:141], v[66:69], v[204:207], v[138:141]
	v_mfma_f32_16x16x32_bf16 v[142:145], v[158:161], v[204:207], v[142:145]
	v_mfma_f32_16x16x32_bf16 v[122:125], v[66:69], v[212:215], v[122:125]
	v_mfma_f32_16x16x32_bf16 v[126:129], v[158:161], v[212:215], v[126:129]
	v_mfma_f32_16x16x32_bf16 v[106:109], v[66:69], v[220:223], v[106:109]
	v_mfma_f32_16x16x32_bf16 v[110:113], v[158:161], v[220:223], v[110:113]
	v_mfma_f32_16x16x32_bf16 v[90:93], v[66:69], v[230:233], v[90:93]
	v_mfma_f32_16x16x32_bf16 v[94:97], v[158:161], v[230:233], v[94:97]
	s_barrier
	s_setprio 0
	s_add_i32 s94, s94, s3
	v_lshl_add_u64 v[180:181], s[88:89], 0, v[0:1]
	s_mov_b32 m0, s94
	ds_read_b128 v[176:179], v184 offset:16384
	ds_read_b128 v[204:207], v184 offset:17408
	ds_read_b128 v[208:211], v184 offset:18432
	ds_read_b128 v[212:215], v184 offset:19456
	ds_read_b128 v[216:219], v184 offset:20480
	ds_read_b128 v[220:223], v184 offset:21504
	ds_read_b128 v[224:227], v184 offset:22528
	ds_read_b128 v[230:233], v184 offset:23552
	global_load_lds_dwordx4 v[180:181], off
	s_add_i32 m0, s94, 0x2000
	v_lshl_add_u64 v[238:239], s[88:89], 0, v[170:171]
	s_add_u32 s88, s88, s6
	s_addc_u32 s89, s89, s7
	s_add_i32 s94, s95, s3
	global_load_lds_dwordx4 v[238:239], off
	v_lshl_add_u64 v[240:241], s[88:89], 0, v[0:1]
	s_mov_b32 m0, s94
	v_lshl_add_u64 v[242:243], s[88:89], 0, v[170:171]
	global_load_lds_dwordx4 v[240:241], off
	s_add_i32 m0, s94, 0x2000
	v_lshl_add_u64 v[244:245], s[54:55], 0, v[166:167]
	global_load_lds_dwordx4 v[242:243], off
	s_mov_b32 m0, s16
	v_lshl_add_u64 v[246:247], s[54:55], 0, v[168:169]
	global_load_lds_dwordx4 v[244:245], off
	s_mov_b32 m0, s17
	s_nop 0
	global_load_lds_dwordx4 v[246:247], off
	s_waitcnt vmcnt(8)
	s_waitcnt lgkmcnt(0)
	s_setprio 1
	s_barrier
; #define PG8_STAGE(bufoff, gbase, voff) do { _Pragma("unroll") for (int _i = 0; _i < 2; ++_i) \
;     __builtin_amdgcn_global_load_lds((const unsigned*)((const char*)(gbase) + (voff)[_i]), (LAS unsigned*)(lds + (bufoff) + ldsw + _i * 8192), 16, 0, 0); } while (0)
; #define PG8_LDA(dst, b, h) do { _Pragma("unroll") for (int m = 0; m < 4; ++m) _Pragma("unroll") for (int k = 0; k < 2; ++k) dst[m][k] = *(const LAS bf16x8*)(lds + PG8_SA(b, h) + aoff + m * 2048 + k * 1024); } while (0)
; #define PG8_LDB(dst, b, h) do { _Pragma("unroll") for (int n = 0; n < 2; ++n) _Pragma("unroll") for (int k = 0; k < 2; ++k) dst[n][k] = *(const LAS bf16x8*)(lds + PG8_SB(b, h) + boff + n * 2048 + k * 1024); } while (0)
; #define PG8_MMA(ai, bj, At, Bt) do { __builtin_amdgcn_s_setprio(1); _Pragma("unroll") for (int m = 0; m < 4; ++m) _Pragma("unroll") for (int n = 0; n < 2; ++n) _Pragma("unroll") for (int k = 0; k < 2; ++k) \
;     acc[ai][bj][m][n] = __builtin_amdgcn_mfma_f32_16x16x32_bf16(Bt[n][k], At[m][k], acc[ai][bj][m][n], 0, 0, 0); __builtin_amdgcn_s_setprio(0); } while (0)
; #define PG8_WAIT_V(n) asm volatile("s_waitcnt vmcnt(" #n ")" ::: "memory")
; #define PG8_WAIT_L(n) asm volatile("s_waitcnt lgkmcnt(" #n ")" ::: "memory")
; #define PG8_BAR __builtin_amdgcn_s_barrier()
; #define PG8_SCHED __builtin_amdgcn_sched_barrier(0)
; template <class Epi>
; DI void gemm_phase(LAS unsigned char* lds, const Gemm g, const StaticOrder& S, const Epi& E) {
;     ...
;       PG8_WAIT_V(8); PG8_WAIT_L(0); PG8_BAR; PG8_MMA(1, 0, At, B0); PG8_MMA(1, 1, At, B1); PG8_BAR; PG8_SCHED;
;       PG8_LDB(B0, 1, 0); PG8_LDB(B1, 1, 1); PG8_SCHED; PG8_LDA(At, 1, 0); PG8_STAGE(PG8_SA(0, 1), a2 + hstepA, voffA);
;       PG8_WAIT_V(8); PG8_WAIT_L(0); PG8_BAR; PG8_MMA(0, 0, At, B0); PG8_MMA(0, 1, At, B1); PG8_BAR; PG8_SCHED;
;       PG8_LDA(At, 1, 1); PG8_STAGE(PG8_SB(1, 0), b3, voffB); PG8_STAGE(PG8_SB(1, 1), b3 + hstepB, voffB); PG8_STAGE(PG8_SA(1, 0), a3, voffA);
;       PG8_WAIT_V(8); PG8_WAIT_L(0); PG8_BAR; PG8_MMA(1, 0, At, B0); PG8_MMA(1, 1, At, B1); PG8_BAR; PG8_SCHED;
	v_mfma_f32_16x16x32_bf16 v[86:89], v[34:37], v[176:179], v[86:89]
	v_mfma_f32_16x16x32_bf16 v[82:85], v[50:53], v[176:179], v[82:85]
	v_mfma_f32_16x16x32_bf16 v[70:73], v[34:37], v[208:211], v[70:73]
	v_mfma_f32_16x16x32_bf16 v[58:61], v[50:53], v[208:211], v[58:61]
	v_mfma_f32_16x16x32_bf16 v[30:33], v[34:37], v[216:219], v[30:33]
	v_mfma_f32_16x16x32_bf16 v[26:29], v[50:53], v[216:219], v[26:29]
	v_mfma_f32_16x16x32_bf16 v[14:17], v[34:37], v[224:227], v[14:17]
	v_mfma_f32_16x16x32_bf16 v[10:13], v[50:53], v[224:227], v[10:13]
	v_mfma_f32_16x16x32_bf16 v[86:89], v[42:45], v[204:207], v[86:89]
	v_mfma_f32_16x16x32_bf16 v[82:85], v[54:57], v[204:207], v[82:85]
	v_mfma_f32_16x16x32_bf16 v[70:73], v[42:45], v[212:215], v[70:73]
	v_mfma_f32_16x16x32_bf16 v[58:61], v[54:57], v[212:215], v[58:61]
	v_mfma_f32_16x16x32_bf16 v[30:33], v[42:45], v[220:223], v[30:33]
	v_mfma_f32_16x16x32_bf16 v[26:29], v[54:57], v[220:223], v[26:29]
	v_mfma_f32_16x16x32_bf16 v[14:17], v[42:45], v[230:233], v[14:17]
	v_mfma_f32_16x16x32_bf16 v[10:13], v[54:57], v[230:233], v[10:13]
	v_mfma_f32_16x16x32_bf16 v[38:41], v[62:65], v[208:211], v[38:41]
	v_mfma_f32_16x16x32_bf16 v[46:49], v[154:157], v[208:211], v[46:49]
	v_mfma_f32_16x16x32_bf16 v[18:21], v[62:65], v[216:219], v[18:21]
	v_mfma_f32_16x16x32_bf16 v[22:25], v[154:157], v[216:219], v[22:25]
	v_mfma_f32_16x16x32_bf16 v[2:5], v[62:65], v[224:227], v[2:5]
	v_mfma_f32_16x16x32_bf16 v[6:9], v[154:157], v[224:227], v[6:9]
	v_mfma_f32_16x16x32_bf16 v[34:37], v[62:65], v[176:179], v[74:77]
	v_mfma_f32_16x16x32_bf16 v[42:45], v[154:157], v[176:179], v[78:81]
	v_mfma_f32_16x16x32_bf16 v[38:41], v[66:69], v[212:215], v[38:41]
	v_mfma_f32_16x16x32_bf16 v[46:49], v[158:161], v[212:215], v[46:49]
	v_mfma_f32_16x16x32_bf16 v[18:21], v[66:69], v[220:223], v[18:21]
	v_mfma_f32_16x16x32_bf16 v[22:25], v[158:161], v[220:223], v[22:25]
	v_mfma_f32_16x16x32_bf16 v[2:5], v[66:69], v[230:233], v[2:5]
	v_mfma_f32_16x16x32_bf16 v[6:9], v[158:161], v[230:233], v[6:9]
	v_mfma_f32_16x16x32_bf16 v[34:37], v[66:69], v[204:207], v[34:37]
	v_mfma_f32_16x16x32_bf16 v[42:45], v[158:161], v[204:207], v[42:45]
	s_barrier
	s_setprio 0
	s_add_i32 s88, 0, 0x18000
	s_add_i32 s89, 0, 0x1c000
	v_add_u32_e32 v66, s88, v182
	v_add_u32_e32 v74, s89, v182
	ds_read_b128 v[50:53], v66
	ds_read_b128 v[54:57], v66 offset:1024
	ds_read_b128 v[62:65], v66 offset:2048
	ds_read_b128 v[66:69], v66 offset:3072
	ds_read_b128 v[154:157], v74
	ds_read_b128 v[158:161], v74 offset:1024
	ds_read_b128 v[176:179], v74 offset:2048
	ds_read_b128 v[204:207], v74 offset:3072
	s_add_u32 s54, s54, s4
	s_addc_u32 s55, s55, s5
	s_mov_b32 m0, s33
	v_lshl_add_u64 v[234:235], s[54:55], 0, v[166:167]
	ds_read_b128 v[74:77], v184 offset:32768
	ds_read_b128 v[78:81], v184 offset:33792
	ds_read_b128 v[208:211], v184 offset:34816
	ds_read_b128 v[212:215], v184 offset:35840
	ds_read_b128 v[216:219], v184 offset:36864
	ds_read_b128 v[220:223], v184 offset:37888
	ds_read_b128 v[224:227], v184 offset:38912
	ds_read_b128 v[230:233], v184 offset:39936
	global_load_lds_dwordx4 v[234:235], off
	v_lshl_add_u64 v[234:235], s[54:55], 0, v[168:169]
	s_mov_b32 m0, s56
	s_nop 0
	global_load_lds_dwordx4 v[234:235], off
	s_waitcnt vmcnt(8)
	s_waitcnt lgkmcnt(0)
	s_setprio 1
	s_barrier
	v_mfma_f32_16x16x32_bf16 v[150:153], v[50:53], v[74:77], v[150:153]
	v_mfma_f32_16x16x32_bf16 v[146:149], v[62:65], v[74:77], v[146:149]
	v_mfma_f32_16x16x32_bf16 v[134:137], v[50:53], v[208:211], v[134:137]
	v_mfma_f32_16x16x32_bf16 v[130:133], v[62:65], v[208:211], v[130:133]
	v_mfma_f32_16x16x32_bf16 v[118:121], v[50:53], v[216:219], v[118:121]
	v_mfma_f32_16x16x32_bf16 v[114:117], v[62:65], v[216:219], v[114:117]
	v_mfma_f32_16x16x32_bf16 v[102:105], v[50:53], v[224:227], v[102:105]
	v_mfma_f32_16x16x32_bf16 v[98:101], v[62:65], v[224:227], v[98:101]
	v_mfma_f32_16x16x32_bf16 v[150:153], v[54:57], v[78:81], v[150:153]
	v_mfma_f32_16x16x32_bf16 v[146:149], v[66:69], v[78:81], v[146:149]
	v_mfma_f32_16x16x32_bf16 v[134:137], v[54:57], v[212:215], v[134:137]
	v_mfma_f32_16x16x32_bf16 v[130:133], v[66:69], v[212:215], v[130:133]
	v_mfma_f32_16x16x32_bf16 v[118:121], v[54:57], v[220:223], v[118:121]
	v_mfma_f32_16x16x32_bf16 v[114:117], v[66:69], v[220:223], v[114:117]
	v_mfma_f32_16x16x32_bf16 v[102:105], v[54:57], v[230:233], v[102:105]
	v_mfma_f32_16x16x32_bf16 v[98:101], v[66:69], v[230:233], v[98:101]
	v_mfma_f32_16x16x32_bf16 v[138:141], v[154:157], v[74:77], v[138:141]
	v_mfma_f32_16x16x32_bf16 v[74:77], v[176:179], v[74:77], v[142:145]
	v_mfma_f32_16x16x32_bf16 v[142:145], v[204:207], v[78:81], v[74:77]
	v_mfma_f32_16x16x32_bf16 v[74:77], v[154:157], v[208:211], v[122:125]
	v_mfma_f32_16x16x32_bf16 v[122:125], v[158:161], v[212:215], v[74:77]
	v_mfma_f32_16x16x32_bf16 v[74:77], v[176:179], v[208:211], v[126:129]
	v_mfma_f32_16x16x32_bf16 v[126:129], v[204:207], v[212:215], v[74:77]
	v_mfma_f32_16x16x32_bf16 v[74:77], v[154:157], v[216:219], v[106:109]
	v_mfma_f32_16x16x32_bf16 v[106:109], v[158:161], v[220:223], v[74:77]
	v_mfma_f32_16x16x32_bf16 v[74:77], v[176:179], v[216:219], v[110:113]
	v_mfma_f32_16x16x32_bf16 v[110:113], v[204:207], v[220:223], v[74:77]
	v_mfma_f32_16x16x32_bf16 v[74:77], v[154:157], v[224:227], v[90:93]
	v_mfma_f32_16x16x32_bf16 v[90:93], v[158:161], v[230:233], v[74:77]
	v_mfma_f32_16x16x32_bf16 v[74:77], v[176:179], v[224:227], v[94:97]
	v_mfma_f32_16x16x32_bf16 v[138:141], v[158:161], v[78:81], v[138:141]
	v_mfma_f32_16x16x32_bf16 v[94:97], v[204:207], v[230:233], v[74:77]
	s_barrier
; #define PG8_STAGE(bufoff, gbase, voff) do { _Pragma("unroll") for (int _i = 0; _i < 2; ++_i) \
;     __builtin_amdgcn_global_load_lds((const unsigned*)((const char*)(gbase) + (voff)[_i]), (LAS unsigned*)(lds + (bufoff) + ldsw + _i * 8192), 16, 0, 0); } while (0)
; #define PG8_LDA(dst, b, h) do { _Pragma("unroll") for (int m = 0; m < 4; ++m) _Pragma("unroll") for (int k = 0; k < 2; ++k) dst[m][k] = *(const LAS bf16x8*)(lds + PG8_SA(b, h) + aoff + m * 2048 + k * 1024); } while (0)
; #define PG8_MMA(ai, bj, At, Bt) do { __builtin_amdgcn_s_setprio(1); _Pragma("unroll") for (int m = 0; m < 4; ++m) _Pragma("unroll") for (int n = 0; n < 2; ++n) _Pragma("unroll") for (int k = 0; k < 2; ++k) \
;     acc[ai][bj][m][n] = __builtin_amdgcn_mfma_f32_16x16x32_bf16(Bt[n][k], At[m][k], acc[ai][bj][m][n], 0, 0, 0); __builtin_amdgcn_s_setprio(0); } while (0)
; #define PG8_WAIT_V(n) asm volatile("s_waitcnt vmcnt(" #n ")" ::: "memory")
; #define PG8_WAIT_L(n) asm volatile("s_waitcnt lgkmcnt(" #n ")" ::: "memory")
; #define PG8_BAR __builtin_amdgcn_s_barrier()
; #define PG8_SCHED __builtin_amdgcn_sched_barrier(0)
; template <class Epi>
; DI void gemm_phase(LAS unsigned char* lds, const Gemm g, const StaticOrder& S, const Epi& E) {
;     ...
;     for (int t = 0; t < nt; t += 2) {
;       const bool last = (t == nt - 2);
;       const char* a1 = cA + (size_t)(t + 1) * kstep;
;       const char* a2 = last ? nA : cA + (size_t)(t + 2) * kstep; const char* b2 = last ? nB : cB + (size_t)(t + 2) * kstep;
;       const char* a3 = a2 + kstep; const char* b3 = b2 + kstep;
;     ...
;       PG8_LDA(At, 1, 1); PG8_STAGE(PG8_SB(1, 0), b3, voffB); PG8_STAGE(PG8_SB(1, 1), b3 + hstepB, voffB); PG8_STAGE(PG8_SA(1, 0), a3, voffA);
;       PG8_WAIT_V(8); PG8_WAIT_L(0); PG8_BAR; PG8_MMA(1, 0, At, B0); PG8_MMA(1, 1, At, B1); PG8_BAR; PG8_SCHED;
	s_setprio 0
	s_add_i32 s54, s88, s3
	s_nop 2
	v_lshl_add_u64 v[74:75], v[180:181], 0, s[38:39]
	s_mov_b32 m0, s54
	ds_read_b128 v[78:81], v184 offset:49152
	ds_read_b128 v[208:211], v184 offset:50176
	ds_read_b128 v[212:215], v184 offset:51200
	ds_read_b128 v[216:219], v184 offset:52224
	ds_read_b128 v[220:223], v184 offset:53248
	ds_read_b128 v[224:227], v184 offset:54272
	ds_read_b128 v[230:233], v184 offset:55296
	ds_read_b128 v[234:237], v184 offset:56320
	global_load_lds_dwordx4 v[74:75], off
	v_lshl_add_u64 v[74:75], v[238:239], 0, s[38:39]
	s_add_i32 m0, s54, 0x2000
	s_add_i32 s54, s89, s3
	global_load_lds_dwordx4 v[74:75], off
	v_lshl_add_u64 v[74:75], v[240:241], 0, s[38:39]
	s_mov_b32 m0, s54
	s_nop 0
	global_load_lds_dwordx4 v[74:75], off
	v_lshl_add_u64 v[74:75], v[242:243], 0, s[38:39]
	s_add_i32 m0, s54, 0x2000
	s_nop 0
	global_load_lds_dwordx4 v[74:75], off
	v_lshl_add_u64 v[74:75], v[244:245], 0, s[38:39]
	s_mov_b32 m0, s58
	s_nop 0
	global_load_lds_dwordx4 v[74:75], off
	v_lshl_add_u64 v[74:75], v[246:247], 0, s[38:39]
	s_mov_b32 m0, s68
	s_nop 0
	global_load_lds_dwordx4 v[74:75], off
	s_waitcnt vmcnt(8)
	s_waitcnt lgkmcnt(0)
	s_setprio 1
	s_barrier
	v_mfma_f32_16x16x32_bf16 v[74:77], v[50:53], v[78:81], v[86:89]
	v_mfma_f32_16x16x32_bf16 v[86:89], v[54:57], v[208:211], v[74:77]
	v_mfma_f32_16x16x32_bf16 v[74:77], v[62:65], v[78:81], v[82:85]
	v_mfma_f32_16x16x32_bf16 v[70:73], v[50:53], v[212:215], v[70:73]
	v_mfma_f32_16x16x32_bf16 v[58:61], v[62:65], v[212:215], v[58:61]
	v_mfma_f32_16x16x32_bf16 v[30:33], v[50:53], v[220:223], v[30:33]
	v_mfma_f32_16x16x32_bf16 v[26:29], v[62:65], v[220:223], v[26:29]
	v_mfma_f32_16x16x32_bf16 v[14:17], v[50:53], v[230:233], v[14:17]
	v_mfma_f32_16x16x32_bf16 v[10:13], v[62:65], v[230:233], v[10:13]
	v_mfma_f32_16x16x32_bf16 v[82:85], v[66:69], v[208:211], v[74:77]
	v_mfma_f32_16x16x32_bf16 v[70:73], v[54:57], v[216:219], v[70:73]
	v_mfma_f32_16x16x32_bf16 v[58:61], v[66:69], v[216:219], v[58:61]
	v_mfma_f32_16x16x32_bf16 v[30:33], v[54:57], v[224:227], v[30:33]
	v_mfma_f32_16x16x32_bf16 v[26:29], v[66:69], v[224:227], v[26:29]
	v_mfma_f32_16x16x32_bf16 v[14:17], v[54:57], v[234:237], v[14:17]
	v_mfma_f32_16x16x32_bf16 v[10:13], v[66:69], v[234:237], v[10:13]
	v_mfma_f32_16x16x32_bf16 v[34:37], v[154:157], v[78:81], v[34:37]
	v_mfma_f32_16x16x32_bf16 v[74:77], v[158:161], v[208:211], v[34:37]
	v_mfma_f32_16x16x32_bf16 v[34:37], v[176:179], v[78:81], v[42:45]
	v_mfma_f32_16x16x32_bf16 v[78:81], v[204:207], v[208:211], v[34:37]
	v_mfma_f32_16x16x32_bf16 v[34:37], v[154:157], v[212:215], v[38:41]
	v_mfma_f32_16x16x32_bf16 v[38:41], v[158:161], v[216:219], v[34:37]
	v_mfma_f32_16x16x32_bf16 v[34:37], v[176:179], v[212:215], v[46:49]
	v_mfma_f32_16x16x32_bf16 v[18:21], v[154:157], v[220:223], v[18:21]
	v_mfma_f32_16x16x32_bf16 v[22:25], v[176:179], v[220:223], v[22:25]
	v_mfma_f32_16x16x32_bf16 v[2:5], v[154:157], v[230:233], v[2:5]
	v_mfma_f32_16x16x32_bf16 v[6:9], v[176:179], v[230:233], v[6:9]
	v_mfma_f32_16x16x32_bf16 v[46:49], v[204:207], v[216:219], v[34:37]
	v_mfma_f32_16x16x32_bf16 v[18:21], v[158:161], v[224:227], v[18:21]
	v_mfma_f32_16x16x32_bf16 v[22:25], v[204:207], v[224:227], v[22:25]
	v_mfma_f32_16x16x32_bf16 v[2:5], v[158:161], v[234:237], v[2:5]
	v_mfma_f32_16x16x32_bf16 v[6:9], v[204:207], v[234:237], v[6:9]
	s_barrier
	s_setprio 0
	s_add_u32 s42, s42, 0x100
	s_addc_u32 s43, s43, 0
	s_add_u32 s62, s62, 0x100
	s_addc_u32 s63, s63, 0
	s_cmp_ge_i32 s87, s57
	s_mov_b32 s54, s87
	s_cbranch_scc0 .LBB0_555
	s_movk_i32 s88, 0xc00

; #define PG8_STAGE(bufoff, gbase, voff) do { _Pragma("unroll") for (int _i = 0; _i < 2; ++_i) \
;     __builtin_amdgcn_global_load_lds((const unsigned*)((const char*)(gbase) + (voff)[_i]), (LAS unsigned*)(lds + (bufoff) + ldsw + _i * 8192), 16, 0, 0); } while (0)
; #define PG8_LDA(dst, b, h) do { _Pragma("unroll") for (int m = 0; m < 4; ++m) _Pragma("unroll") for (int k = 0; k < 2; ++k) dst[m][k] = *(const LAS bf16x8*)(lds + PG8_SA(b, h) + aoff + m * 2048 + k * 1024); } while (0)
; #define PG8_LDB(dst, b, h) do { _Pragma("unroll") for (int n = 0; n < 2; ++n) _Pragma("unroll") for (int k = 0; k < 2; ++k) dst[n][k] = *(const LAS bf16x8*)(lds + PG8_SB(b, h) + boff + n * 2048 + k * 1024); } while (0)
; #define PG8_MMA(ai, bj, At, Bt) do { __builtin_amdgcn_s_setprio(1); _Pragma("unroll") for (int m = 0; m < 4; ++m) _Pragma("unroll") for (int n = 0; n < 2; ++n) _Pragma("unroll") for (int k = 0; k < 2; ++k) \
;     acc[ai][bj][m][n] = __builtin_amdgcn_mfma_f32_16x16x32_bf16(Bt[n][k], At[m][k], acc[ai][bj][m][n], 0, 0, 0); __builtin_amdgcn_s_setprio(0); } while (0)
; #define PG8_WAIT_V(n) asm volatile("s_waitcnt vmcnt(" #n ")" ::: "memory")
; #define PG8_WAIT_L(n) asm volatile("s_waitcnt lgkmcnt(" #n ")" ::: "memory")
; #define PG8_BAR __builtin_amdgcn_s_barrier()
; #define PG8_SCHED __builtin_amdgcn_sched_barrier(0)
; template <class Epi>
; DI void gemm_phase(LAS unsigned char* lds, const Gemm g, const StaticOrder& S, const Epi& E) {
;     ...
;     for (int t = 0; t < nt; t += 2) {
;       const bool last = (t == nt - 2);
;       const char* a1 = cA + (size_t)(t + 1) * kstep;
;       const char* a2 = last ? nA : cA + (size_t)(t + 2) * kstep; const char* b2 = last ? nB : cB + (size_t)(t + 2) * kstep;
;       const char* a3 = a2 + kstep; const char* b3 = b2 + kstep;
;       PG8_LDB(B0, 0, 0); PG8_LDB(B1, 0, 1); PG8_SCHED; PG8_LDA(At, 0, 0); PG8_STAGE(PG8_SA(1, 1), a1 + hstepA, voffA);
;       PG8_WAIT_V(8); PG8_WAIT_L(0); PG8_BAR; PG8_MMA(0, 0, At, B0); PG8_MMA(0, 1, At, B1); PG8_BAR; PG8_SCHED;
;       PG8_LDA(At, 0, 1); PG8_STAGE(PG8_SB(0, 0), b2, voffB); PG8_STAGE(PG8_SB(0, 1), b2 + hstepB, voffB); PG8_STAGE(PG8_SA(0, 0), a2, voffA);
;       PG8_WAIT_V(8); PG8_WAIT_L(0); PG8_BAR; PG8_MMA(1, 0, At, B0); PG8_MMA(1, 1, At, B1); PG8_BAR; PG8_SCHED;
.LBB0_844:
	s_add_i32 s49, s46, 2
	s_add_u32 s50, s44, 0x80
	s_addc_u32 s47, s45, 0
	s_add_i32 s52, 0, 0x10000
	s_cmp_eq_u32 s33, s46
	s_cselect_b32 s47, s13, s47
	s_cselect_b32 s46, s12, s50
	s_cselect_b32 s51, s85, s48
	s_cselect_b32 s50, s84, s23
	s_add_i32 s53, 0, 0x14000
	v_add_u32_e32 v156, s52, v178
	v_add_u32_e32 v160, s53, v178
	ds_read_b128 v[130:133], v156
	ds_read_b128 v[134:137], v156 offset:1024
	ds_read_b128 v[152:155], v156 offset:2048
	ds_read_b128 v[156:159], v156 offset:3072
	ds_read_b128 v[166:169], v160
	ds_read_b128 v[170:173], v160 offset:1024
	ds_read_b128 v[174:177], v160 offset:2048
	ds_read_b128 v[182:185], v160 offset:3072
	v_lshl_add_u64 v[160:161], s[44:45], 0, v[148:149]
	s_add_i32 m0, s54, 0xc000
	ds_read_b128 v[204:207], v180
	ds_read_b128 v[208:211], v180 offset:1024
	ds_read_b128 v[212:215], v180 offset:2048
	ds_read_b128 v[216:219], v180 offset:3072
	ds_read_b128 v[220:223], v180 offset:4096
	ds_read_b128 v[224:227], v180 offset:5120
	ds_read_b128 v[230:233], v180 offset:6144
	ds_read_b128 v[234:237], v180 offset:7168
	global_load_lds_dwordx4 v[160:161], off
	v_lshl_add_u64 v[160:161], s[44:45], 0, v[150:151]
	s_add_i32 m0, s54, 0xe000
	s_nop 0
	global_load_lds_dwordx4 v[160:161], off
	s_waitcnt vmcnt(8)
	s_waitcnt lgkmcnt(0)
	s_setprio 1
	s_barrier
	v_mfma_f32_16x16x32_bf16 v[126:129], v[130:133], v[204:207], v[126:129]
	v_mfma_f32_16x16x32_bf16 v[122:125], v[152:155], v[204:207], v[122:125]
	v_mfma_f32_16x16x32_bf16 v[110:113], v[130:133], v[212:215], v[110:113]
	v_mfma_f32_16x16x32_bf16 v[106:109], v[152:155], v[212:215], v[106:109]
	v_mfma_f32_16x16x32_bf16 v[94:97], v[130:133], v[220:223], v[94:97]
	v_mfma_f32_16x16x32_bf16 v[90:93], v[152:155], v[220:223], v[90:93]
	v_mfma_f32_16x16x32_bf16 v[78:81], v[130:133], v[230:233], v[78:81]
	v_mfma_f32_16x16x32_bf16 v[74:77], v[152:155], v[230:233], v[74:77]
	v_mfma_f32_16x16x32_bf16 v[126:129], v[134:137], v[208:211], v[126:129]
	v_mfma_f32_16x16x32_bf16 v[122:125], v[156:159], v[208:211], v[122:125]
	v_mfma_f32_16x16x32_bf16 v[110:113], v[134:137], v[216:219], v[110:113]
	v_mfma_f32_16x16x32_bf16 v[106:109], v[156:159], v[216:219], v[106:109]
	v_mfma_f32_16x16x32_bf16 v[94:97], v[134:137], v[224:227], v[94:97]
	v_mfma_f32_16x16x32_bf16 v[90:93], v[156:159], v[224:227], v[90:93]
	v_mfma_f32_16x16x32_bf16 v[78:81], v[134:137], v[234:237], v[78:81]
	v_mfma_f32_16x16x32_bf16 v[74:77], v[156:159], v[234:237], v[74:77]
	v_mfma_f32_16x16x32_bf16 v[118:121], v[166:169], v[204:207], v[118:121]
	v_mfma_f32_16x16x32_bf16 v[114:117], v[174:177], v[204:207], v[114:117]
	v_mfma_f32_16x16x32_bf16 v[102:105], v[166:169], v[212:215], v[102:105]
	v_mfma_f32_16x16x32_bf16 v[98:101], v[174:177], v[212:215], v[98:101]
	v_mfma_f32_16x16x32_bf16 v[86:89], v[166:169], v[220:223], v[86:89]
	v_mfma_f32_16x16x32_bf16 v[82:85], v[174:177], v[220:223], v[82:85]
	v_mfma_f32_16x16x32_bf16 v[70:73], v[166:169], v[230:233], v[70:73]
	v_mfma_f32_16x16x32_bf16 v[66:69], v[174:177], v[230:233], v[66:69]
	v_mfma_f32_16x16x32_bf16 v[118:121], v[170:173], v[208:211], v[118:121]
	v_mfma_f32_16x16x32_bf16 v[114:117], v[182:185], v[208:211], v[114:117]
	v_mfma_f32_16x16x32_bf16 v[102:105], v[170:173], v[216:219], v[102:105]
	v_mfma_f32_16x16x32_bf16 v[98:101], v[182:185], v[216:219], v[98:101]
	v_mfma_f32_16x16x32_bf16 v[86:89], v[170:173], v[224:227], v[86:89]
	v_mfma_f32_16x16x32_bf16 v[82:85], v[182:185], v[224:227], v[82:85]
	v_mfma_f32_16x16x32_bf16 v[70:73], v[170:173], v[234:237], v[70:73]
	v_mfma_f32_16x16x32_bf16 v[66:69], v[182:185], v[234:237], v[66:69]
	s_barrier
	s_setprio 0
	s_add_i32 s52, s52, s17
	v_lshl_add_u64 v[160:161], s[50:51], 0, v[140:141]
	s_mov_b32 m0, s52
	ds_read_b128 v[204:207], v180 offset:16384
	ds_read_b128 v[208:211], v180 offset:17408
	ds_read_b128 v[212:215], v180 offset:18432
	ds_read_b128 v[216:219], v180 offset:19456
	ds_read_b128 v[220:223], v180 offset:20480
	ds_read_b128 v[224:227], v180 offset:21504
	ds_read_b128 v[230:233], v180 offset:22528
	ds_read_b128 v[234:237], v180 offset:23552
	global_load_lds_dwordx4 v[160:161], off
	s_add_i32 m0, s52, 0x2000
	v_lshl_add_u64 v[238:239], s[50:51], 0, v[144:145]
	s_add_u32 s50, s50, s94
	s_addc_u32 s51, s51, s95
	s_add_i32 s52, s53, s17
	global_load_lds_dwordx4 v[238:239], off
	v_lshl_add_u64 v[240:241], s[50:51], 0, v[140:141]
	s_mov_b32 m0, s52
	v_lshl_add_u64 v[242:243], s[50:51], 0, v[144:145]
	global_load_lds_dwordx4 v[240:241], off
	s_add_i32 m0, s52, 0x2000
	v_lshl_add_u64 v[244:245], s[46:47], 0, v[138:139]
	global_load_lds_dwordx4 v[242:243], off
	s_mov_b32 m0, s54
	v_lshl_add_u64 v[246:247], s[46:47], 0, v[142:143]
	global_load_lds_dwordx4 v[244:245], off
	s_mov_b32 m0, s55
	s_nop 0
	global_load_lds_dwordx4 v[246:247], off
	s_waitcnt vmcnt(8)
	s_waitcnt lgkmcnt(0)
	s_setprio 1
	s_barrier
; #define PG8_STAGE(bufoff, gbase, voff) do { _Pragma("unroll") for (int _i = 0; _i < 2; ++_i) \
;     __builtin_amdgcn_global_load_lds((const unsigned*)((const char*)(gbase) + (voff)[_i]), (LAS unsigned*)(lds + (bufoff) + ldsw + _i * 8192), 16, 0, 0); } while (0)
; #define PG8_LDA(dst, b, h) do { _Pragma("unroll") for (int m = 0; m < 4; ++m) _Pragma("unroll") for (int k = 0; k < 2; ++k) dst[m][k] = *(const LAS bf16x8*)(lds + PG8_SA(b, h) + aoff + m * 2048 + k * 1024); } while (0)
; #define PG8_LDB(dst, b, h) do { _Pragma("unroll") for (int n = 0; n < 2; ++n) _Pragma("unroll") for (int k = 0; k < 2; ++k) dst[n][k] = *(const LAS bf16x8*)(lds + PG8_SB(b, h) + boff + n * 2048 + k * 1024); } while (0)
; #define PG8_MMA(ai, bj, At, Bt) do { __builtin_amdgcn_s_setprio(1); _Pragma("unroll") for (int m = 0; m < 4; ++m) _Pragma("unroll") for (int n = 0; n < 2; ++n) _Pragma("unroll") for (int k = 0; k < 2; ++k) \
;     acc[ai][bj][m][n] = __builtin_amdgcn_mfma_f32_16x16x32_bf16(Bt[n][k], At[m][k], acc[ai][bj][m][n], 0, 0, 0); __builtin_amdgcn_s_setprio(0); } while (0)
; #define PG8_WAIT_V(n) asm volatile("s_waitcnt vmcnt(" #n ")" ::: "memory")
; #define PG8_WAIT_L(n) asm volatile("s_waitcnt lgkmcnt(" #n ")" ::: "memory")
; #define PG8_BAR __builtin_amdgcn_s_barrier()
; #define PG8_SCHED __builtin_amdgcn_sched_barrier(0)
; template <class Epi>
; DI void gemm_phase(LAS unsigned char* lds, const Gemm g, const StaticOrder& S, const Epi& E) {
;     ...
;       PG8_WAIT_V(8); PG8_WAIT_L(0); PG8_BAR; PG8_MMA(1, 0, At, B0); PG8_MMA(1, 1, At, B1); PG8_BAR; PG8_SCHED;
;       PG8_LDB(B0, 1, 0); PG8_LDB(B1, 1, 1); PG8_SCHED; PG8_LDA(At, 1, 0); PG8_STAGE(PG8_SA(0, 1), a2 + hstepA, voffA);
;       PG8_WAIT_V(8); PG8_WAIT_L(0); PG8_BAR; PG8_MMA(0, 0, At, B0); PG8_MMA(0, 1, At, B1); PG8_BAR; PG8_SCHED;
;       PG8_LDA(At, 1, 1); PG8_STAGE(PG8_SB(1, 0), b3, voffB); PG8_STAGE(PG8_SB(1, 1), b3 + hstepB, voffB); PG8_STAGE(PG8_SA(1, 0), a3, voffA);
;       PG8_WAIT_V(8); PG8_WAIT_L(0); PG8_BAR; PG8_MMA(1, 0, At, B0); PG8_MMA(1, 1, At, B1); PG8_BAR; PG8_SCHED;
	v_mfma_f32_16x16x32_bf16 v[62:65], v[130:133], v[204:207], v[62:65]
	v_mfma_f32_16x16x32_bf16 v[58:61], v[152:155], v[204:207], v[58:61]
	v_mfma_f32_16x16x32_bf16 v[46:49], v[130:133], v[212:215], v[46:49]
	v_mfma_f32_16x16x32_bf16 v[42:45], v[152:155], v[212:215], v[42:45]
	v_mfma_f32_16x16x32_bf16 v[30:33], v[130:133], v[220:223], v[30:33]
	v_mfma_f32_16x16x32_bf16 v[26:29], v[152:155], v[220:223], v[26:29]
	v_mfma_f32_16x16x32_bf16 v[14:17], v[130:133], v[230:233], v[14:17]
	v_mfma_f32_16x16x32_bf16 v[10:13], v[152:155], v[230:233], v[10:13]
	v_mfma_f32_16x16x32_bf16 v[62:65], v[134:137], v[208:211], v[62:65]
	v_mfma_f32_16x16x32_bf16 v[58:61], v[156:159], v[208:211], v[58:61]
	v_mfma_f32_16x16x32_bf16 v[46:49], v[134:137], v[216:219], v[46:49]
	v_mfma_f32_16x16x32_bf16 v[42:45], v[156:159], v[216:219], v[42:45]
	v_mfma_f32_16x16x32_bf16 v[30:33], v[134:137], v[224:227], v[30:33]
	v_mfma_f32_16x16x32_bf16 v[26:29], v[156:159], v[224:227], v[26:29]
	v_mfma_f32_16x16x32_bf16 v[14:17], v[134:137], v[234:237], v[14:17]
	v_mfma_f32_16x16x32_bf16 v[10:13], v[156:159], v[234:237], v[10:13]
	v_mfma_f32_16x16x32_bf16 v[54:57], v[166:169], v[204:207], v[54:57]
	v_mfma_f32_16x16x32_bf16 v[50:53], v[174:177], v[204:207], v[50:53]
	v_mfma_f32_16x16x32_bf16 v[38:41], v[166:169], v[212:215], v[38:41]
	v_mfma_f32_16x16x32_bf16 v[34:37], v[174:177], v[212:215], v[34:37]
	v_mfma_f32_16x16x32_bf16 v[22:25], v[166:169], v[220:223], v[22:25]
	v_mfma_f32_16x16x32_bf16 v[18:21], v[174:177], v[220:223], v[18:21]
	v_mfma_f32_16x16x32_bf16 v[6:9], v[166:169], v[230:233], v[6:9]
	v_mfma_f32_16x16x32_bf16 v[2:5], v[174:177], v[230:233], v[2:5]
	v_mfma_f32_16x16x32_bf16 v[54:57], v[170:173], v[208:211], v[54:57]
	v_mfma_f32_16x16x32_bf16 v[50:53], v[182:185], v[208:211], v[50:53]
	v_mfma_f32_16x16x32_bf16 v[38:41], v[170:173], v[216:219], v[38:41]
	v_mfma_f32_16x16x32_bf16 v[34:37], v[182:185], v[216:219], v[34:37]
	v_mfma_f32_16x16x32_bf16 v[22:25], v[170:173], v[224:227], v[22:25]
	v_mfma_f32_16x16x32_bf16 v[18:21], v[182:185], v[224:227], v[18:21]
	v_mfma_f32_16x16x32_bf16 v[6:9], v[170:173], v[234:237], v[6:9]
	v_mfma_f32_16x16x32_bf16 v[2:5], v[182:185], v[234:237], v[2:5]
	s_barrier
	s_setprio 0
	s_add_i32 s50, 0, 0x18000
	s_add_i32 s51, 0, 0x1c000
	v_add_u32_e32 v156, s50, v178
	v_add_u32_e32 v181, s51, v178
	ds_read_b128 v[130:133], v156
	ds_read_b128 v[134:137], v156 offset:1024
	ds_read_b128 v[152:155], v156 offset:2048
	ds_read_b128 v[156:159], v156 offset:3072
	ds_read_b128 v[166:169], v181
	ds_read_b128 v[170:173], v181 offset:1024
	ds_read_b128 v[174:177], v181 offset:2048
	ds_read_b128 v[182:185], v181 offset:3072
	s_add_u32 s46, s46, s20
	s_addc_u32 s47, s47, s21
	s_mov_b32 m0, s14
	v_lshl_add_u64 v[248:249], s[46:47], 0, v[138:139]
	ds_read_b128 v[204:207], v180 offset:32768
	ds_read_b128 v[208:211], v180 offset:33792
	ds_read_b128 v[212:215], v180 offset:34816
	ds_read_b128 v[216:219], v180 offset:35840
	ds_read_b128 v[220:223], v180 offset:36864
	ds_read_b128 v[224:227], v180 offset:37888
	ds_read_b128 v[230:233], v180 offset:38912
	ds_read_b128 v[234:237], v180 offset:39936
	global_load_lds_dwordx4 v[248:249], off
	v_lshl_add_u64 v[248:249], s[46:47], 0, v[142:143]
	s_mov_b32 m0, s15
	s_nop 0
	global_load_lds_dwordx4 v[248:249], off
	s_waitcnt vmcnt(8)
	s_waitcnt lgkmcnt(0)
	s_setprio 1
	s_barrier
	v_mfma_f32_16x16x32_bf16 v[126:129], v[130:133], v[204:207], v[126:129]
	v_mfma_f32_16x16x32_bf16 v[122:125], v[152:155], v[204:207], v[122:125]
	v_mfma_f32_16x16x32_bf16 v[110:113], v[130:133], v[212:215], v[110:113]
	v_mfma_f32_16x16x32_bf16 v[106:109], v[152:155], v[212:215], v[106:109]
	v_mfma_f32_16x16x32_bf16 v[94:97], v[130:133], v[220:223], v[94:97]
	v_mfma_f32_16x16x32_bf16 v[90:93], v[152:155], v[220:223], v[90:93]
	v_mfma_f32_16x16x32_bf16 v[78:81], v[130:133], v[230:233], v[78:81]
	v_mfma_f32_16x16x32_bf16 v[74:77], v[152:155], v[230:233], v[74:77]
	v_mfma_f32_16x16x32_bf16 v[126:129], v[134:137], v[208:211], v[126:129]
	v_mfma_f32_16x16x32_bf16 v[122:125], v[156:159], v[208:211], v[122:125]
	v_mfma_f32_16x16x32_bf16 v[110:113], v[134:137], v[216:219], v[110:113]
	v_mfma_f32_16x16x32_bf16 v[106:109], v[156:159], v[216:219], v[106:109]
	v_mfma_f32_16x16x32_bf16 v[94:97], v[134:137], v[224:227], v[94:97]
	v_mfma_f32_16x16x32_bf16 v[90:93], v[156:159], v[224:227], v[90:93]
	v_mfma_f32_16x16x32_bf16 v[78:81], v[134:137], v[234:237], v[78:81]
	v_mfma_f32_16x16x32_bf16 v[74:77], v[156:159], v[234:237], v[74:77]
	v_mfma_f32_16x16x32_bf16 v[118:121], v[166:169], v[204:207], v[118:121]
	v_mfma_f32_16x16x32_bf16 v[114:117], v[174:177], v[204:207], v[114:117]
	v_mfma_f32_16x16x32_bf16 v[102:105], v[166:169], v[212:215], v[102:105]
	v_mfma_f32_16x16x32_bf16 v[98:101], v[174:177], v[212:215], v[98:101]
	v_mfma_f32_16x16x32_bf16 v[86:89], v[166:169], v[220:223], v[86:89]
	v_mfma_f32_16x16x32_bf16 v[82:85], v[174:177], v[220:223], v[82:85]
	v_mfma_f32_16x16x32_bf16 v[70:73], v[166:169], v[230:233], v[70:73]
	v_mfma_f32_16x16x32_bf16 v[66:69], v[174:177], v[230:233], v[66:69]
	v_mfma_f32_16x16x32_bf16 v[118:121], v[170:173], v[208:211], v[118:121]
	v_mfma_f32_16x16x32_bf16 v[114:117], v[182:185], v[208:211], v[114:117]
	v_mfma_f32_16x16x32_bf16 v[102:105], v[170:173], v[216:219], v[102:105]
	v_mfma_f32_16x16x32_bf16 v[98:101], v[182:185], v[216:219], v[98:101]
	v_mfma_f32_16x16x32_bf16 v[86:89], v[170:173], v[224:227], v[86:89]
	v_mfma_f32_16x16x32_bf16 v[82:85], v[182:185], v[224:227], v[82:85]
	v_mfma_f32_16x16x32_bf16 v[70:73], v[170:173], v[234:237], v[70:73]
	v_mfma_f32_16x16x32_bf16 v[66:69], v[182:185], v[234:237], v[66:69]
	s_barrier
; #define PG8_STAGE(bufoff, gbase, voff) do { _Pragma("unroll") for (int _i = 0; _i < 2; ++_i) \
;     __builtin_amdgcn_global_load_lds((const unsigned*)((const char*)(gbase) + (voff)[_i]), (LAS unsigned*)(lds + (bufoff) + ldsw + _i * 8192), 16, 0, 0); } while (0)
; #define PG8_LDA(dst, b, h) do { _Pragma("unroll") for (int m = 0; m < 4; ++m) _Pragma("unroll") for (int k = 0; k < 2; ++k) dst[m][k] = *(const LAS bf16x8*)(lds + PG8_SA(b, h) + aoff + m * 2048 + k * 1024); } while (0)
; #define PG8_MMA(ai, bj, At, Bt) do { __builtin_amdgcn_s_setprio(1); _Pragma("unroll") for (int m = 0; m < 4; ++m) _Pragma("unroll") for (int n = 0; n < 2; ++n) _Pragma("unroll") for (int k = 0; k < 2; ++k) \
;     acc[ai][bj][m][n] = __builtin_amdgcn_mfma_f32_16x16x32_bf16(Bt[n][k], At[m][k], acc[ai][bj][m][n], 0, 0, 0); __builtin_amdgcn_s_setprio(0); } while (0)
; #define PG8_WAIT_V(n) asm volatile("s_waitcnt vmcnt(" #n ")" ::: "memory")
; #define PG8_WAIT_L(n) asm volatile("s_waitcnt lgkmcnt(" #n ")" ::: "memory")
; #define PG8_BAR __builtin_amdgcn_s_barrier()
; #define PG8_SCHED __builtin_amdgcn_sched_barrier(0)
; template <class Epi>
; DI void gemm_phase(LAS unsigned char* lds, const Gemm g, const StaticOrder& S, const Epi& E) {
;     ...
;     for (int t = 0; t < nt; t += 2) {
;       const bool last = (t == nt - 2);
;       const char* a1 = cA + (size_t)(t + 1) * kstep;
;       const char* a2 = last ? nA : cA + (size_t)(t + 2) * kstep; const char* b2 = last ? nB : cB + (size_t)(t + 2) * kstep;
;       const char* a3 = a2 + kstep; const char* b3 = b2 + kstep;
;     ...
;       PG8_LDA(At, 1, 1); PG8_STAGE(PG8_SB(1, 0), b3, voffB); PG8_STAGE(PG8_SB(1, 1), b3 + hstepB, voffB); PG8_STAGE(PG8_SA(1, 0), a3, voffA);
;       PG8_WAIT_V(8); PG8_WAIT_L(0); PG8_BAR; PG8_MMA(1, 0, At, B0); PG8_MMA(1, 1, At, B1); PG8_BAR; PG8_SCHED;
	s_setprio 0
	s_add_i32 s46, s50, s17
	v_lshl_add_u64 v[160:161], v[160:161], 0, s[38:39]
	s_mov_b32 m0, s46
	ds_read_b128 v[204:207], v180 offset:49152
	ds_read_b128 v[208:211], v180 offset:50176
	ds_read_b128 v[212:215], v180 offset:51200
	ds_read_b128 v[216:219], v180 offset:52224
	ds_read_b128 v[220:223], v180 offset:53248
	ds_read_b128 v[224:227], v180 offset:54272
	ds_read_b128 v[230:233], v180 offset:55296
	ds_read_b128 v[234:237], v180 offset:56320
	global_load_lds_dwordx4 v[160:161], off
	v_lshl_add_u64 v[160:161], v[238:239], 0, s[38:39]
	s_add_i32 m0, s46, 0x2000
	s_add_i32 s46, s51, s17
	global_load_lds_dwordx4 v[160:161], off
	v_lshl_add_u64 v[160:161], v[240:241], 0, s[38:39]
	s_mov_b32 m0, s46
	s_nop 0
	global_load_lds_dwordx4 v[160:161], off
	v_lshl_add_u64 v[160:161], v[242:243], 0, s[38:39]
	s_add_i32 m0, s46, 0x2000
	s_nop 0
	global_load_lds_dwordx4 v[160:161], off
	v_lshl_add_u64 v[160:161], v[244:245], 0, s[38:39]
	s_mov_b32 m0, s6
	s_nop 0
	global_load_lds_dwordx4 v[160:161], off
	v_lshl_add_u64 v[160:161], v[246:247], 0, s[38:39]
	s_mov_b32 m0, s7
	s_nop 0
	global_load_lds_dwordx4 v[160:161], off
	s_waitcnt vmcnt(8)
	s_waitcnt lgkmcnt(0)
	s_setprio 1
	s_barrier
	v_mfma_f32_16x16x32_bf16 v[62:65], v[130:133], v[204:207], v[62:65]
	v_mfma_f32_16x16x32_bf16 v[58:61], v[152:155], v[204:207], v[58:61]
	v_mfma_f32_16x16x32_bf16 v[46:49], v[130:133], v[212:215], v[46:49]
	v_mfma_f32_16x16x32_bf16 v[42:45], v[152:155], v[212:215], v[42:45]
	v_mfma_f32_16x16x32_bf16 v[30:33], v[130:133], v[220:223], v[30:33]
	v_mfma_f32_16x16x32_bf16 v[26:29], v[152:155], v[220:223], v[26:29]
	v_mfma_f32_16x16x32_bf16 v[14:17], v[130:133], v[230:233], v[14:17]
	v_mfma_f32_16x16x32_bf16 v[10:13], v[152:155], v[230:233], v[10:13]
	v_mfma_f32_16x16x32_bf16 v[62:65], v[134:137], v[208:211], v[62:65]
	v_mfma_f32_16x16x32_bf16 v[58:61], v[156:159], v[208:211], v[58:61]
	v_mfma_f32_16x16x32_bf16 v[46:49], v[134:137], v[216:219], v[46:49]
	v_mfma_f32_16x16x32_bf16 v[42:45], v[156:159], v[216:219], v[42:45]
	v_mfma_f32_16x16x32_bf16 v[30:33], v[134:137], v[224:227], v[30:33]
	v_mfma_f32_16x16x32_bf16 v[26:29], v[156:159], v[224:227], v[26:29]
	v_mfma_f32_16x16x32_bf16 v[14:17], v[134:137], v[234:237], v[14:17]
	v_mfma_f32_16x16x32_bf16 v[10:13], v[156:159], v[234:237], v[10:13]
	v_mfma_f32_16x16x32_bf16 v[54:57], v[166:169], v[204:207], v[54:57]
	v_mfma_f32_16x16x32_bf16 v[50:53], v[174:177], v[204:207], v[50:53]
	v_mfma_f32_16x16x32_bf16 v[38:41], v[166:169], v[212:215], v[38:41]
	v_mfma_f32_16x16x32_bf16 v[34:37], v[174:177], v[212:215], v[34:37]
	v_mfma_f32_16x16x32_bf16 v[22:25], v[166:169], v[220:223], v[22:25]
	v_mfma_f32_16x16x32_bf16 v[18:21], v[174:177], v[220:223], v[18:21]
	v_mfma_f32_16x16x32_bf16 v[6:9], v[166:169], v[230:233], v[6:9]
	v_mfma_f32_16x16x32_bf16 v[2:5], v[174:177], v[230:233], v[2:5]
	v_mfma_f32_16x16x32_bf16 v[54:57], v[170:173], v[208:211], v[54:57]
	v_mfma_f32_16x16x32_bf16 v[50:53], v[182:185], v[208:211], v[50:53]
	v_mfma_f32_16x16x32_bf16 v[38:41], v[170:173], v[216:219], v[38:41]
	v_mfma_f32_16x16x32_bf16 v[34:37], v[182:185], v[216:219], v[34:37]
	v_mfma_f32_16x16x32_bf16 v[22:25], v[170:173], v[224:227], v[22:25]
	v_mfma_f32_16x16x32_bf16 v[18:21], v[182:185], v[224:227], v[18:21]
	v_mfma_f32_16x16x32_bf16 v[6:9], v[170:173], v[234:237], v[6:9]
	v_mfma_f32_16x16x32_bf16 v[2:5], v[182:185], v[234:237], v[2:5]
	s_barrier
	s_setprio 0
	s_add_u32 s44, s44, 0x100
	s_addc_u32 s45, s45, 0
	s_add_u32 s23, s23, 0x100
	s_addc_u32 s48, s48, 0
	s_cmp_ge_i32 s49, s16
	s_mov_b32 s46, s49
	s_cbranch_scc0 .LBB0_844
